# static wave priority in the attention phase too: waves 0-3 at s_setprio 1 (two-half de-phasing of the wave pairs sharing a SIMD), as in the scan
# speedup vs baseline: 1.0092x; 1.0003x over previous
.LBB0_2650:
	s_or_b64 exec, exec, s[0:1]
	s_add_u32 s60, s84, 0x7a988c0
	s_addc_u32 s61, s85, 0
	v_mov_b32_e32 v38, v174
	s_cmpk_gt_i32 s2, 0x1ff
	s_waitcnt lgkmcnt(0)
	s_barrier
	s_cselect_b32 s99, 1, 0
	s_setprio 0
	v_readfirstlane_b32 s98, v174
	s_lshr_b32 s98, s98, 6
	s_cmp_ge_u32 s98, 4
	s_cbranch_scc1 .Lpr13_skip
	s_setprio 1
.Lpr13_skip:
	s_cmp_lg_u32 s99, 0
	s_cbranch_scc1 .LBB0_2698
	v_and_b32_e32 v4, 31, v38
	s_mov_b32 s3, 0x55555556
	v_lshlrev_b32_e32 v43, 3, v4
	s_waitcnt vmcnt(0)
	v_lshl_add_u32 v8, v4, 4, 0
	v_mul_hi_i32 v4, v38, s3
	v_lshrrev_b32_e32 v5, 31, v4
	v_ashrrev_i32_e32 v41, 6, v38
	s_movk_i32 s0, 0x1500
	v_add_u32_e32 v4, v4, v5
	s_movk_i32 s3, 0x230
	v_mul_lo_u32 v0, v41, s0
	s_add_i32 s0, 0, 0x11c00
	v_lshl_add_u32 v5, v4, 1, v4
	v_mul_lo_u32 v4, v4, s3
	v_add_u32_e32 v3, s0, v0
	v_sub_u32_e32 v5, v38, v5
	v_add_u32_e32 v9, 0, v4
	v_bfe_u32 v4, v38, 2, 4
	s_movk_i32 s4, 0x150
	v_lshlrev_b32_e32 v10, 4, v5
	v_lshlrev_b32_e32 v5, 3, v38
	v_mad_u32_u24 v12, v4, s4, v3
	v_ashrrev_i32_e32 v4, 5, v38
	v_and_b32_e32 v11, 24, v5
	v_ashrrev_i32_e32 v5, 31, v4
	v_lshlrev_b64 v[52:53], 13, v[4:5]
	v_mul_lo_u32 v17, v4, s3
	v_add_u32_e32 v4, 0x200, v38
	v_ashrrev_i32_e32 v49, 3, v4
	v_ashrrev_i32_e32 v4, 5, v4
	v_ashrrev_i32_e32 v5, 31, v4
	v_lshlrev_b64 v[54:55], 13, v[4:5]
	v_mul_lo_u32 v19, v4, s3
	v_add_u32_e32 v4, 0x400, v38
	v_bfe_u32 v6, v38, 4, 2
	v_ashrrev_i32_e32 v61, 3, v4
	v_ashrrev_i32_e32 v4, 5, v4
	v_and_b32_e32 v1, 15, v38
	v_lshlrev_b32_e32 v48, 2, v6
	v_ashrrev_i32_e32 v5, 31, v4
	v_and_b32_e32 v42, 64, v38
	v_lshlrev_b32_e32 v46, 1, v1
	v_lshlrev_b64 v[56:57], 13, v[4:5]
	v_mul_lo_u32 v21, v4, s3
	v_add_u32_e32 v4, 0x600, v38
	v_or_b32_e32 v24, 2, v48
	v_and_b32_e32 v13, 48, v38
	v_add_u32_e32 v15, v3, v46
	v_mad_u32_u24 v3, v1, s4, v3
	v_ashrrev_i32_e32 v45, 3, v38
	s_movk_i32 s4, 0x90
	v_ashrrev_i32_e32 v63, 3, v4
	v_ashrrev_i32_e32 v4, 5, v4
	v_or_b32_e32 v60, 16, v42
	v_or_b32_e32 v62, 32, v42
	v_or_b32_e32 v64, 48, v42
	v_or_b32_e32 v23, 1, v48
	v_cmp_ge_u32_e64 s[14:15], v1, v24
	v_cmp_gt_u32_e64 s[16:17], v1, v24
	v_or_b32_e32 v24, 3, v48
	v_and_b32_e32 v44, 0x4f, v38
	v_and_b32_e32 v2, 7, v38
	v_add_u32_e32 v14, 0, v13
	v_mul_lo_u32 v16, v45, s4
	v_mul_lo_u32 v18, v49, s4
	v_mul_lo_u32 v20, v61, s4
	v_mul_lo_u32 v22, v63, s4
	v_ashrrev_i32_e32 v5, 31, v4
	v_cmp_ge_u32_e64 s[4:5], v1, v48
	v_cmp_gt_u32_e64 s[6:7], v1, v48
	v_cmp_gt_u32_e64 s[12:13], v1, v23
	v_cmp_ge_u32_e64 s[18:19], v1, v24
	v_cmp_gt_u32_e64 s[20:21], v1, v24
	v_mul_u32_u24_e32 v25, 0x230, v1
	v_or_b32_e32 v26, v60, v1
	v_or_b32_e32 v28, v62, v1
	v_or_b32_e32 v1, v64, v1
	v_mov_b32_e32 v47, 0
	v_lshlrev_b32_e32 v0, 3, v6
	v_lshl_add_u32 v7, v2, 4, 0
	v_lshlrev_b32_e32 v2, 3, v2
	s_movk_i32 s0, 0xc0
	v_lshlrev_b64 v[58:59], 13, v[4:5]
	v_mul_lo_u32 v4, v4, s3
	v_mul_u32_u24_e32 v5, 0x90, v44
	v_mul_u32_u24_e32 v6, 0x540, v6
	v_mul_u32_u24_e32 v23, 0x150, v23
	v_lshl_add_u32 v24, v42, 1, v14
	v_mul_u32_u24_e32 v26, 0x90, v26
	v_lshl_add_u32 v27, v60, 1, v14
	v_mul_u32_u24_e32 v28, 0x90, v28
	v_lshl_add_u32 v29, v62, 1, v14
	v_mul_u32_u24_e32 v1, 0x90, v1
	v_lshl_add_u32 v30, v64, 1, v14
	v_and_b32_e32 v40, 63, v38
	v_ashrrev_i32_e32 v39, 7, v38
	v_cmp_gt_i32_e64 s[0:1], s0, v38
	v_lshl_add_u64 v[50:51], s[60:61], 0, v[46:47]
	v_cmp_ne_u32_e64 s[8:9], 0, v42
	v_lshlrev_b32_e32 v46, 1, v0
	s_mov_b32 s3, 0x8000
	s_mov_b32 s38, 0x10000
	s_mov_b32 s39, 0x18000
	v_lshlrev_b32_e32 v66, 1, v2
	v_add_u32_e32 v65, v7, v16
	v_add_u32_e32 v76, v8, v17
	v_add_u32_e32 v77, v7, v18
	v_add_u32_e32 v78, v8, v19
	v_add_u32_e32 v79, v7, v20
	v_add_u32_e32 v80, v8, v21
	v_add_u32_e32 v81, v7, v22
	v_add_u32_e32 v82, v8, v4
	v_add_u32_e32 v83, v9, v10
	v_add_u32_e32 v84, v12, v11
	v_add_u32_e32 v85, v14, v5
	s_mov_b32 s42, 0x3e000000
	s_movk_i32 s43, 0x7fff
	v_add_u32_e32 v86, v15, v6
	v_add_u32_e32 v87, v15, v23
	v_add_u32_e32 v88, v3, v13
	v_add_u32_e32 v89, v24, v25
	s_movk_i32 s44, 0x880
	v_add_u32_e32 v90, v14, v26
	v_add_u32_e32 v91, v27, v25
	v_add_u32_e32 v92, v14, v28
	v_add_u32_e32 v93, v29, v25
	v_add_u32_e32 v94, v14, v1
	v_add_u32_e32 v95, v30, v25
	v_mov_b32_e32 v98, v47
	v_mov_b32_e32 v99, v47
	v_mov_b32_e32 v100, v47
	v_mov_b32_e32 v101, v47
	v_mov_b32_e32 v102, v47
	v_mov_b32_e32 v103, v47
	v_mov_b32_e32 v96, 0xff800000
	s_mov_b32 s45, s2
	s_branch .LBB0_2653
